# softmax half-step: fewer VALU ops (max tree, per-half row sum combined once per block, fused l update, scalar path flag)
# speedup vs baseline: 1.0050x; 1.0025x over previous
; __device__ __forceinline__ void attn_block(const Ptrs& P, int b, int h, int qb, LAS char* lds) {
;     ...
;         float pmax = p0[0];
; #pragma unroll
;         for (int r = 1; r < 16; ++r) pmax = fmaxf(pmax, p0[r]);
; #pragma unroll
;         for (int r = 0; r < 16; ++r) pmax = fmaxf(pmax, p1[r]);
;         { auto sw_ = __builtin_amdgcn_permlane32_swap(__float_as_uint(pmax), __float_as_uint(pmax), false, false); pmax = fmaxf(__uint_as_float(sw_[0]), __uint_as_float(sw_[1])); }
;         float alpha = 1.f;
;         if (!__all(pmax - m_reg <= THRL)) { const float mn = fmaxf(m_reg, pmax); alpha = __builtin_amdgcn_exp2f(m_reg - mn); m_reg = mn; }
.LBB0_619:
	s_nop 6
	v_max3_f32 v199, v84, v85, v86
	v_max3_f32 v199, v199, v87, v88
	v_max3_f32 v199, v199, v89, v90
	v_max3_f32 v199, v199, v91, v92
	v_max3_f32 v199, v199, v93, v94
	v_max3_f32 v199, v199, v95, v96
	v_max3_f32 v199, v199, v97, v98
	v_max3_f32 v199, v199, v99, v68
	v_max3_f32 v199, v199, v69, v70
	v_max3_f32 v199, v199, v71, v72
	v_max3_f32 v199, v199, v73, v74
	v_max3_f32 v199, v199, v75, v76
	v_max3_f32 v199, v199, v77, v78
	v_max3_f32 v199, v199, v79, v80
	v_max3_f32 v199, v199, v81, v82
	v_max_f32_e32 v199, v199, v83
	v_mov_b32_e32 v200, v199
	s_nop 1
	v_permlane32_swap_b32_e32 v199, v200
	v_max_f32_e32 v199, v199, v200
	v_cmp_ge_f32_e32 vcc, s68, v199
	s_andn2_b64 s[22:23], vcc, s[56:57]
	s_cmp_eq_u64 s[22:23], exec
	s_cbranch_scc1 .Lattn_fast
	v_max_f32_e32 v200, 0, v199
	v_cndmask_b32_e64 v200, v200, v199, s[56:57]
	v_add_f32_e32 v196, v196, v200
	v_sub_f32_e32 v84, v84, v200
	v_sub_f32_e32 v85, v85, v200
	v_sub_f32_e32 v86, v86, v200
	v_sub_f32_e32 v87, v87, v200
	v_sub_f32_e32 v88, v88, v200
	v_sub_f32_e32 v89, v89, v200
	v_sub_f32_e32 v90, v90, v200
	v_sub_f32_e32 v91, v91, v200
	v_sub_f32_e32 v92, v92, v200
	v_sub_f32_e32 v93, v93, v200
	v_sub_f32_e32 v94, v94, v200
	v_sub_f32_e32 v95, v95, v200
	v_sub_f32_e32 v96, v96, v200
	v_sub_f32_e32 v97, v97, v200
	v_sub_f32_e32 v98, v98, v200
	v_sub_f32_e32 v99, v99, v200
	v_sub_f32_e32 v68, v68, v200
	v_sub_f32_e32 v69, v69, v200
	v_sub_f32_e32 v70, v70, v200
	v_sub_f32_e32 v71, v71, v200
	v_sub_f32_e32 v72, v72, v200
	v_sub_f32_e32 v73, v73, v200
	v_sub_f32_e32 v74, v74, v200
	v_sub_f32_e32 v75, v75, v200
	v_sub_f32_e32 v76, v76, v200
	v_sub_f32_e32 v77, v77, v200
	v_sub_f32_e32 v78, v78, v200
	v_sub_f32_e32 v79, v79, v200
	v_sub_f32_e32 v80, v80, v200
	v_sub_f32_e32 v81, v81, v200
	v_sub_f32_e32 v82, v82, v200
	v_sub_f32_e32 v83, v83, v200
	v_sub_f32_e32 v224, v224, v200
	v_sub_f32_e32 v225, v225, v200
	v_sub_f32_e32 v226, v226, v200
	v_sub_f32_e32 v227, v227, v200
	v_sub_f32_e32 v228, v228, v200
	v_sub_f32_e32 v229, v229, v200
	v_sub_f32_e32 v230, v230, v200
	v_sub_f32_e32 v231, v231, v200
	v_sub_f32_e32 v232, v232, v200
	v_sub_f32_e32 v233, v233, v200
	v_sub_f32_e32 v234, v234, v200
	v_sub_f32_e32 v235, v235, v200
	v_sub_f32_e32 v236, v236, v200
	v_sub_f32_e32 v237, v237, v200
	v_sub_f32_e32 v238, v238, v200
	v_sub_f32_e32 v239, v239, v200
	v_sub_f32_e32 v201, 0, v200
	v_exp_f32_e32 v201, v201
	s_nop 0
	v_cndmask_b32_e64 v200, v201, 0, s[56:57]
	s_branch .Lattn_exp

; __device__ __forceinline__ int crow(int r, int hi) { return (r & 3) + 8 * (r >> 2) + 4 * hi; }
; __device__ __forceinline__ void attn_block(const Ptrs& P, int b, int h, int qb, LAS char* lds) {
;     ...
; #pragma unroll
;         for (int r = 0; r < 16; ++r) { p0[r] = __builtin_amdgcn_exp2f(p0[r] - m_reg); p1[r] = __builtin_amdgcn_exp2f(p1[r] - m_reg); }
;         float ps = 0.f;
; #pragma unroll
;         for (int r = 0; r < 16; ++r) ps += p0[r];
; #pragma unroll
;         for (int r = 0; r < 16; ++r) ps += p1[r];
;         { auto sw_ = __builtin_amdgcn_permlane32_swap(__float_as_uint(ps), __float_as_uint(ps), false, false); ps = __uint_as_float(sw_[0]) + __uint_as_float(sw_[1]); }
;         l_reg = l_reg * alpha + ps;
;         PK4(p0, 0, pa0); PK4(p0, 8, pa1); PK4(p1, 0, pa2); PK4(p1, 8, pa3);
;         if (__any(alpha < 1.f)) { if (hi == 0) al_l[r32] = alpha; asm volatile("s_waitcnt lgkmcnt(0)" ::: "memory");
; #pragma unroll
;             for (int d_ = 0; d_ < 4; ++d_)
; #pragma unroll
;                 for (int r = 0; r < 16; ++r) o[d_][r] *= al_l[crow(r, hi)]; }
.Lattn_exp:
	v_exp_f32_e32 v84, v84
	v_exp_f32_e32 v85, v85
	v_exp_f32_e32 v86, v86
	v_exp_f32_e32 v87, v87
	v_exp_f32_e32 v88, v88
	v_exp_f32_e32 v89, v89
	v_exp_f32_e32 v90, v90
	v_exp_f32_e32 v91, v91
	v_exp_f32_e32 v92, v92
	v_exp_f32_e32 v93, v93
	v_exp_f32_e32 v94, v94
	v_exp_f32_e32 v95, v95
	v_exp_f32_e32 v96, v96
	v_exp_f32_e32 v97, v97
	v_exp_f32_e32 v98, v98
	v_exp_f32_e32 v99, v99
	v_exp_f32_e32 v68, v68
	v_add_f32_e32 v199, v84, v85
	v_exp_f32_e32 v69, v69
	v_add_f32_e32 v201, v86, v87
	v_exp_f32_e32 v70, v70
	v_add_f32_e32 v202, v88, v89
	v_exp_f32_e32 v71, v71
	v_add_f32_e32 v203, v90, v91
	v_exp_f32_e32 v72, v72
	v_add_f32_e32 v199, v92, v199
	v_exp_f32_e32 v73, v73
	v_add_f32_e32 v201, v93, v201
	v_exp_f32_e32 v74, v74
	v_add_f32_e32 v202, v94, v202
	v_exp_f32_e32 v75, v75
	v_add_f32_e32 v203, v95, v203
	v_exp_f32_e32 v76, v76
	v_add_f32_e32 v199, v96, v199
	v_exp_f32_e32 v77, v77
	v_add_f32_e32 v201, v97, v201
	v_exp_f32_e32 v78, v78
	v_add_f32_e32 v202, v98, v202
	v_exp_f32_e32 v79, v79
	v_add_f32_e32 v203, v99, v203
	v_exp_f32_e32 v80, v80
	v_exp_f32_e32 v81, v81
	v_exp_f32_e32 v82, v82
	v_exp_f32_e32 v83, v83
	v_add_f32_e32 v199, v68, v199
	v_add_f32_e32 v201, v69, v201
	v_add_f32_e32 v202, v70, v202
	v_add_f32_e32 v203, v71, v203
	v_add_f32_e32 v199, v72, v199
	v_add_f32_e32 v201, v73, v201
	v_add_f32_e32 v202, v74, v202
	v_add_f32_e32 v203, v75, v203
	v_add_f32_e32 v199, v76, v199
	v_add_f32_e32 v201, v77, v201
	v_add_f32_e32 v202, v78, v202
	v_add_f32_e32 v203, v79, v203
	v_add_f32_e32 v199, v80, v199
	v_add_f32_e32 v201, v81, v201
	v_add_f32_e32 v202, v82, v202
	v_add_f32_e32 v203, v83, v203
	v_add_f32_e32 v199, v199, v201
	v_add_f32_e32 v202, v202, v203
	v_cvt_pk_bf16_f32 v83, v82, v83
	v_cvt_pk_bf16_f32 v82, v80, v81
	v_cvt_pk_bf16_f32 v81, v78, v79
	v_cvt_pk_bf16_f32 v80, v76, v77
	v_cvt_pk_bf16_f32 v76, v68, v69
	v_cvt_pk_bf16_f32 v77, v70, v71
	v_cvt_pk_bf16_f32 v78, v72, v73
	v_cvt_pk_bf16_f32 v79, v74, v75
	v_cvt_pk_bf16_f32 v68, v84, v85
	v_cvt_pk_bf16_f32 v69, v86, v87
	v_cvt_pk_bf16_f32 v70, v88, v89
	v_cvt_pk_bf16_f32 v71, v90, v91
	v_add_f32_e32 v85, v199, v202
	v_mov_b32_e32 v84, v200
	v_cvt_pk_bf16_f32 v72, v92, v93
	v_cvt_pk_bf16_f32 v73, v94, v95
	v_cvt_pk_bf16_f32 v74, v96, v97
	v_cvt_pk_bf16_f32 v75, v98, v99
	s_cmp_eq_u64 s[22:23], exec
	s_cbranch_scc1 .LBB0_623
	s_and_saveexec_b64 s[22:23], s[0:1]
	ds_write_b32 v194, v84 offset:128
	s_or_b64 exec, exec, s[22:23]
	s_waitcnt lgkmcnt(0)
	ds_read_b128 v[88:91], v193 offset:224
	ds_read_b128 v[92:95], v193 offset:192
	ds_read_b128 v[96:99], v193 offset:160
	ds_read_b128 v[200:203], v193 offset:128
	s_waitcnt lgkmcnt(3)
	v_pk_mul_f32 v[66:67], v[66:67], v[90:91]
	s_waitcnt lgkmcnt(2)
	v_pk_mul_f32 v[62:63], v[62:63], v[94:95]
	s_waitcnt lgkmcnt(1)
	v_pk_mul_f32 v[58:59], v[58:59], v[98:99]
	s_waitcnt lgkmcnt(0)
	v_pk_mul_f32 v[54:55], v[54:55], v[202:203]
	v_pk_mul_f32 v[64:65], v[64:65], v[88:89]
	v_pk_mul_f32 v[60:61], v[60:61], v[92:93]
	v_pk_mul_f32 v[56:57], v[56:57], v[96:97]
	v_pk_mul_f32 v[52:53], v[52:53], v[200:201]
	v_pk_mul_f32 v[50:51], v[50:51], v[90:91]
	v_pk_mul_f32 v[46:47], v[46:47], v[94:95]
	v_pk_mul_f32 v[42:43], v[42:43], v[98:99]
	v_pk_mul_f32 v[38:39], v[38:39], v[202:203]
	v_pk_mul_f32 v[48:49], v[48:49], v[88:89]
	v_pk_mul_f32 v[44:45], v[44:45], v[92:93]
	v_pk_mul_f32 v[40:41], v[40:41], v[96:97]
	v_pk_mul_f32 v[36:37], v[36:37], v[200:201]
	v_pk_mul_f32 v[34:35], v[34:35], v[90:91]
	v_pk_mul_f32 v[30:31], v[30:31], v[94:95]
	v_pk_mul_f32 v[26:27], v[26:27], v[98:99]
	v_pk_mul_f32 v[22:23], v[22:23], v[202:203]
	v_pk_mul_f32 v[32:33], v[32:33], v[88:89]
	v_pk_mul_f32 v[28:29], v[28:29], v[92:93]
	v_pk_mul_f32 v[24:25], v[24:25], v[96:97]
	v_pk_mul_f32 v[20:21], v[20:21], v[200:201]
	v_pk_mul_f32 v[18:19], v[18:19], v[90:91]
	v_pk_mul_f32 v[14:15], v[14:15], v[94:95]
	v_pk_mul_f32 v[10:11], v[10:11], v[98:99]
	v_pk_mul_f32 v[6:7], v[6:7], v[202:203]
	v_pk_mul_f32 v[16:17], v[16:17], v[88:89]
	v_pk_mul_f32 v[12:13], v[12:13], v[92:93]
	v_pk_mul_f32 v[8:9], v[8:9], v[96:97]
	v_pk_mul_f32 v[4:5], v[4:5], v[200:201]

; #define SBAR() __builtin_amdgcn_sched_barrier(0)
; __device__ __forceinline__ int crow(int r, int hi) { return (r & 3) + 8 * (r >> 2) + 4 * hi; }
; #define SLOAD(t) do { const int so_ = (t) * (KVBLK * 256); \
;         st_k0 = BLD(srdK, gofk, so_); st_k1 = BLD(srdK, gofk, so_ + 8192); st_v0 = BLD(srdV, gofk, so_); st_v1 = BLD(srdV, gofk, so_ + 8192); st_r = BLD(srdR, gofr, (t) * (KVBLK * 128)); } while (0)
; #define SWRITE(ts, v3) do { const int kb_ = ((ts) & 1) * SHM_K, rb_ = ((ts) & 1) * SHM_R, vb_ = (v3) * SHM_V; \
;         *(LAS bf16x8*)(lds + kb_ + kws) = st_k0; *(LAS bf16x8*)(lds + kb_ + kws + 32 * 256) = st_k1; \
;         *(LAS bf16x8*)(lds + vb_ + vst0) = st_v0; *(LAS bf16x8*)(lds + vb_ + vst1) = st_v1; *(LAS bf16x8*)(lds + rb_ + rws) = st_r; } while (0)
; __device__ __forceinline__ void attn_block(const Ptrs& P, int b, int h, int qb, LAS char* lds) {
;     ...
;         l_reg = l_reg * alpha + ps;
;         PK4(p0, 0, pa0); PK4(p0, 8, pa1); PK4(p1, 0, pa2); PK4(p1, 8, pa3);
;         if (__any(alpha < 1.f)) { if (hi == 0) al_l[r32] = alpha; asm volatile("s_waitcnt lgkmcnt(0)" ::: "memory");
; #pragma unroll
;             for (int d_ = 0; d_ < 4; ++d_)
; #pragma unroll
;                 for (int r = 0; r < 16; ++r) o[d_][r] *= al_l[crow(r, hi)]; }
;         if (ts < NT) SWRITE(ts, ts3);
;         if (ts + 1 < NT) SLOAD(ts + 1);
;         ++ts; ts3 = ts3 == 2 ? 0 : ts3 + 1;
;         __syncthreads();
;     }
;     SBAR(); __builtin_amdgcn_s_setprio(1); pv_tile(o, vb0 + pv3 * SHM_V, pa0, pa1, pa2, pa3); __builtin_amdgcn_s_setprio(0); SBAR();
;     __syncthreads();
;     if (!grp) __syncthreads();
;     ...
;     if (hi == 0) li_l[r32] = l_reg; asm volatile("s_waitcnt lgkmcnt(0)" ::: "memory");
;     float rli[16];
; #pragma unroll
;     for (int r = 0; r < 16; ++r) rli[r] = __builtin_amdgcn_rcpf(li_l[crow(r, hi)]);
.LBB0_627:
	s_add_i32 s22, s83, 1
	s_cmp_lg_u32 s83, 2
	s_cselect_b32 s39, s22, 0
	s_and_b64 s[22:23], exec, s[56:57]
	s_cselect_b32 s83, s83, s39
	s_add_i32 s22, s38, 1
	s_cmp_lg_u32 s38, 2
	s_cselect_b32 s38, s22, 0
	s_sub_i32 s81, s81, 64
	s_addk_i32 s78, 0x2000
	s_addk_i32 s79, 0x4000
	s_add_i32 s22, s80, s81
	s_add_i32 s82, s82, 64
	s_add_i32 s77, s77, 1
	v_fma_f32 v198, v198, v84, v85
	v_xor_b32_e32 v3, 0x4000, v3
	v_xor_b32_e32 v197, 0x2000, v197
	s_cmp_eq_u32 s22, 0
	s_waitcnt lgkmcnt(0)
	s_barrier
	s_cbranch_scc1 .LBB0_629
	s_branch .LBB0_615
.LBB0_629:
	v_mov_b32_e32 v85, v198
	v_mov_b32_e32 v86, v198
	s_nop 1
	v_permlane32_swap_b32_e32 v85, v86
	v_add_f32_e32 v85, v85, v86
	s_setprio 1
	v_lshl_add_u32 v3, s83, 14, v182
	ds_read_b64_tr_b16 v[86:87], v3 offset:0
	ds_read_b64_tr_b16 v[88:89], v3 offset:0x800
	ds_read_b64_tr_b16 v[90:91], v3 offset:0x1000
	ds_read_b64_tr_b16 v[92:93], v3 offset:0x1800
	ds_read_b64_tr_b16 v[94:95], v3 offset:0x2000
	ds_read_b64_tr_b16 v[96:97], v3 offset:0x2800
	ds_read_b64_tr_b16 v[98:99], v3 offset:0x3000
	ds_read_b64_tr_b16 v[100:101], v3 offset:0x3800
	s_waitcnt lgkmcnt(0)
	s_nop 0
	v_mfma_f32_32x32x16_bf16 v[52:67], v[68:71], v[86:89], v[52:67]
	ds_read_b64_tr_b16 v[86:87], v3 offset:0x200
	ds_read_b64_tr_b16 v[88:89], v3 offset:0xa00
	v_mfma_f32_32x32x16_bf16 v[52:67], v[72:75], v[90:93], v[52:67]
	ds_read_b64_tr_b16 v[90:91], v3 offset:0x1200
	ds_read_b64_tr_b16 v[92:93], v3 offset:0x1a00
	v_mfma_f32_32x32x16_bf16 v[52:67], v[76:79], v[94:97], v[52:67]
	ds_read_b64_tr_b16 v[94:95], v3 offset:0x2200
	ds_read_b64_tr_b16 v[96:97], v3 offset:0x2a00
	ds_read_b64_tr_b16 v[102:103], v3 offset:0x3200
	ds_read_b64_tr_b16 v[104:105], v3 offset:0x3a00
	s_waitcnt lgkmcnt(0)
	v_mfma_f32_32x32x16_bf16 v[52:67], v[80:83], v[98:101], v[52:67]
	v_mfma_f32_32x32x16_bf16 v[36:51], v[68:71], v[86:89], v[36:51]
	ds_read_b64_tr_b16 v[86:87], v3 offset:0x400
	ds_read_b64_tr_b16 v[88:89], v3 offset:0xc00
	v_mfma_f32_32x32x16_bf16 v[36:51], v[72:75], v[90:93], v[36:51]
	ds_read_b64_tr_b16 v[90:91], v3 offset:0x1400
	ds_read_b64_tr_b16 v[92:93], v3 offset:0x1c00
	v_mfma_f32_32x32x16_bf16 v[36:51], v[76:79], v[94:97], v[36:51]
	ds_read_b64_tr_b16 v[94:95], v3 offset:0x2400
	ds_read_b64_tr_b16 v[96:97], v3 offset:0x2c00
	ds_read_b64_tr_b16 v[98:99], v3 offset:0x3400
	ds_read_b64_tr_b16 v[100:101], v3 offset:0x3c00
	s_waitcnt lgkmcnt(0)
	v_mfma_f32_32x32x16_bf16 v[36:51], v[80:83], v[102:105], v[36:51]
	v_mfma_f32_32x32x16_bf16 v[20:35], v[68:71], v[86:89], v[20:35]
	ds_read_b64_tr_b16 v[86:87], v3 offset:0x600
	ds_read_b64_tr_b16 v[88:89], v3 offset:0xe00
	v_mfma_f32_32x32x16_bf16 v[20:35], v[72:75], v[90:93], v[20:35]
	ds_read_b64_tr_b16 v[90:91], v3 offset:0x1600
	ds_read_b64_tr_b16 v[92:93], v3 offset:0x1e00
	v_mfma_f32_32x32x16_bf16 v[20:35], v[76:79], v[94:97], v[20:35]
	ds_read_b64_tr_b16 v[94:95], v3 offset:0x2600
	ds_read_b64_tr_b16 v[96:97], v3 offset:0x2e00
	ds_read_b64_tr_b16 v[102:103], v3 offset:0x3600
	ds_read_b64_tr_b16 v[104:105], v3 offset:0x3e00
	s_waitcnt lgkmcnt(0)
	v_mfma_f32_32x32x16_bf16 v[20:35], v[80:83], v[98:101], v[20:35]
	v_mfma_f32_32x32x16_bf16 v[4:19], v[68:71], v[86:89], v[4:19]
	v_mfma_f32_32x32x16_bf16 v[4:19], v[72:75], v[90:93], v[4:19]
	v_mfma_f32_32x32x16_bf16 v[4:19], v[76:79], v[94:97], v[4:19]
	v_mfma_f32_32x32x16_bf16 v[4:19], v[80:83], v[102:105], v[4:19]
	s_setprio 0
	s_and_b64 vcc, exec, s[54:55]
	s_barrier
	s_cbranch_vccz .LBB0_631
	s_barrier
